# baseline (speedup 1.0000x reference)
; DI uint2 pack4(float a, float b, float c, float d) { return make_uint2(cvtpk(a, b), cvtpk(c, d)); }
; #define WAIT_L(n) asm volatile("s_waitcnt lgkmcnt(" #n ")":::"memory")
; #define BAR __builtin_amdgcn_s_barrier()
; #define WAIT_L(n) asm volatile("s_waitcnt lgkmcnt(" #n ")":::"memory")
; #define BAR __builtin_amdgcn_s_barrier()
; DI void gemm8_run(const GemmJob& ja, const GemmJob& jb, char* lds) {
;     ...
;               if (r2) { v0 = fmaxf(v0, 0.f); v1 = fmaxf(v1, 0.f); v2 = fmaxf(v2, 0.f); v3 = fmaxf(v3, 0.f); v0 *= v0; v1 *= v1; v2 *= v2; v3 *= v3; }
;               *reinterpret_cast<uint2*>(cst + (wr * 64 + m * 16 + fr) * 528 + (bj * 128 + wc * 32 + n * 16 + fq * 4) * 2) = pack4(v0, v1, v2, v3); } } }
;         WAIT_L(0); BAR;
;         u16* Cb = J.C + (size_t)(brow + ai * 128) * J.ldc + bcol;
; #pragma unroll
;         for (int it = 0; it < 8; ++it) { const int idx = it * 512 + tid; const int r = idx >> 5, c16 = idx & 31;
;           *reinterpret_cast<bf16x8*>(Cb + (size_t)r * J.ldc + c16 * 8) = *reinterpret_cast<const bf16x8*>(cst + r * 528 + c16 * 16); }
;         WAIT_L(0); BAR;
.LBB0_286:
	s_lshl_b64 s[12:13], s[12:13], 1
	s_add_u32 s12, s7, s12
	s_addc_u32 s13, s6, s13
	v_lshlrev_b32_e32 v68, 4, v130
	v_and_b32_e32 v96, 0x1f0, v68
	v_ashrrev_i32_e32 v70, 5, v130
	s_and_b64 s[6:7], s[8:9], exec
	v_cvt_pk_bf16_f32 v64, v64, v65
	v_add_u32_e32 v88, s97, v96
	v_mul_lo_u32 v71, v70, s11
	s_cselect_b32 s6, s52, s58
	v_cvt_pk_bf16_f32 v65, v66, v67
	ds_write_b64 v126, v[64:65] offset:25632
	v_mov_b32_e32 v64, s96
	v_lshl_add_u64 v[68:69], s[12:13], 0, v[96:97]
	v_mul_hi_u32_u24_e32 v65, s6, v64
	v_mul_u32_u24_e32 v64, s6, v64
	v_add_u32_e32 v89, v88, v71
	s_waitcnt lgkmcnt(0)
	s_barrier
	v_lshl_add_u64 v[94:95], v[64:65], 1, v[68:69]
	ds_read_b128 v[64:67], v89
	s_cselect_b32 s2, s53, s59
	v_ashrrev_i32_e32 v71, 31, v70
	v_mul_lo_u32 v71, s6, v71
	v_mul_lo_u32 v72, s2, v70
	v_mad_u64_u32 v[78:79], s[8:9], s6, v70, 0
	v_add3_u32 v79, v79, v71, v72
	v_lshl_add_u64 v[70:71], v[78:79], 1, v[94:95]
	s_waitcnt lgkmcnt(0)
	global_store_dwordx4 v[70:71], v[64:67], off sc1 nt
	s_and_b64 vcc, exec, s[40:41]
	s_nop 0
	v_add_u32_e32 v64, 0x200, v130
	v_ashrrev_i32_e32 v70, 5, v64
	v_mul_lo_u32 v64, v70, s11
	v_add_u32_e32 v87, v88, v64
	ds_read_b128 v[64:67], v87
	v_ashrrev_i32_e32 v71, 31, v70
	v_mul_lo_u32 v71, s6, v71
	v_mul_lo_u32 v72, s2, v70
	v_mad_u64_u32 v[80:81], s[8:9], s6, v70, 0
	v_add3_u32 v81, v81, v71, v72
	v_lshl_add_u64 v[70:71], v[80:81], 1, v[94:95]
	s_waitcnt lgkmcnt(0)
	global_store_dwordx4 v[70:71], v[64:67], off sc1 nt
	s_nop 1
	v_add_u32_e32 v64, 0x400, v130
	v_ashrrev_i32_e32 v70, 5, v64
	v_mul_lo_u32 v64, v70, s11
	v_add_u32_e32 v85, v88, v64
	ds_read_b128 v[64:67], v85
	v_ashrrev_i32_e32 v71, 31, v70
	v_mul_lo_u32 v71, s6, v71
	v_mul_lo_u32 v74, s2, v70
	v_mad_u64_u32 v[72:73], s[8:9], s6, v70, 0
	v_add3_u32 v73, v73, v71, v74
	v_lshl_add_u64 v[70:71], v[72:73], 1, v[94:95]
	s_waitcnt lgkmcnt(0)
	global_store_dwordx4 v[70:71], v[64:67], off sc1 nt
	s_nop 1
	v_add_u32_e32 v64, 0x600, v130
	v_ashrrev_i32_e32 v70, 5, v64
	v_mul_lo_u32 v64, v70, s11
	v_add_u32_e32 v83, v88, v64
	ds_read_b128 v[64:67], v83
	v_ashrrev_i32_e32 v71, 31, v70
	v_mul_lo_u32 v71, s6, v71
	v_mul_lo_u32 v74, s2, v70
	v_mad_u64_u32 v[76:77], s[8:9], s6, v70, 0
	v_add3_u32 v77, v77, v71, v74
	v_lshl_add_u64 v[70:71], v[76:77], 1, v[94:95]
	s_waitcnt lgkmcnt(0)
	global_store_dwordx4 v[70:71], v[64:67], off sc1 nt
	s_nop 1
	v_add_u32_e32 v64, 0x800, v130
	v_ashrrev_i32_e32 v64, 5, v64
	v_mul_lo_u32 v65, v64, s11
	v_add_u32_e32 v82, v88, v65
	ds_read_b128 v[90:93], v82
	v_ashrrev_i32_e32 v65, 31, v64
	v_mul_lo_u32 v66, s6, v65
	v_mul_lo_u32 v67, s2, v64
	v_mad_u64_u32 v[64:65], s[8:9], s6, v64, 0
	v_add3_u32 v65, v65, v66, v67
	v_lshl_add_u64 v[66:67], v[64:65], 1, v[94:95]
	s_waitcnt lgkmcnt(0)
	global_store_dwordx4 v[66:67], v[90:93], off sc1 nt
	v_add_u32_e32 v66, 0xa00, v130
	v_ashrrev_i32_e32 v66, 5, v66
	v_mul_lo_u32 v67, v66, s11
	v_add_u32_e32 v84, v88, v67
	ds_read_b128 v[90:93], v84
	v_ashrrev_i32_e32 v67, 31, v66
	v_mul_lo_u32 v67, s6, v67
	v_mul_lo_u32 v70, s2, v66
	v_mad_u64_u32 v[74:75], s[8:9], s6, v66, 0
	v_add3_u32 v75, v75, v67, v70
	v_lshl_add_u64 v[66:67], v[74:75], 1, v[94:95]
	s_waitcnt lgkmcnt(0)
	global_store_dwordx4 v[66:67], v[90:93], off sc1 nt
	v_add_u32_e32 v66, 0xc00, v130
	v_ashrrev_i32_e32 v66, 5, v66
	v_mul_lo_u32 v67, v66, s11
	v_add_u32_e32 v86, v88, v67
	ds_read_b128 v[90:93], v86
	v_ashrrev_i32_e32 v67, 31, v66
	v_mul_lo_u32 v67, s6, v67
	v_mul_lo_u32 v96, s2, v66
	v_mad_u64_u32 v[70:71], s[8:9], s6, v66, 0
	v_add3_u32 v71, v71, v67, v96
	v_lshl_add_u64 v[66:67], v[70:71], 1, v[94:95]
	s_waitcnt lgkmcnt(0)
	global_store_dwordx4 v[66:67], v[90:93], off sc1 nt
	v_add_u32_e32 v66, 0xe00, v130
	v_ashrrev_i32_e32 v66, 5, v66
	v_mul_lo_u32 v67, v66, s11
	v_add_u32_e32 v88, v88, v67
	ds_read_b128 v[90:93], v88
	v_ashrrev_i32_e32 v67, 31, v66
	v_mul_lo_u32 v96, s6, v67
	v_mul_lo_u32 v98, s2, v66
	v_mad_u64_u32 v[66:67], s[8:9], s6, v66, 0
	v_add3_u32 v67, v67, v96, v98
	v_lshl_add_u64 v[94:95], v[66:67], 1, v[94:95]
	s_waitcnt lgkmcnt(0)
	global_store_dwordx4 v[94:95], v[90:93], off sc1 nt
	s_waitcnt lgkmcnt(0)
	s_barrier
	s_cbranch_vccnz .LBB0_288
	v_max_f32_e32 v60, v60, v60
	v_max_f32_e32 v61, v61, v61
	v_max_f32_e32 v62, v62, v62
	v_max_f32_e32 v63, v63, v63
	v_max_f32_e32 v60, 0, v60
	v_max_f32_e32 v61, 0, v61
	v_max_f32_e32 v62, 0, v62
	v_max_f32_e32 v63, 0, v63
	v_pk_mul_f32 v[60:61], v[60:61], v[60:61]
	v_pk_mul_f32 v[62:63], v[62:63], v[62:63]
